# attention epilogue: all gate loads issued at the epilogue start with clamped rows, lane-transposed via ds_bpermute; output stores transposed (on top of the transposed GEMM epilogues)
# speedup vs baseline: 1.0719x; 1.0116x over previous
; __device__ __forceinline__ float bflo(unsigned v) { return __uint_as_float(v << 16); }
; __device__ __forceinline__ float bfhi(unsigned v) { return __uint_as_float(v & 0xffff0000u); }
; __device__ __forceinline__ float siluf_(float x) { return x * __builtin_amdgcn_rcpf(1.f + __expf(-x)); }
; __device__ __forceinline__ void attn_unit(const WS& ws, int u, bool dry = false) {
;     ...
;   for (int nt = 0; nt < 2; ++nt) {
;     float l = lsum[nt];
;     l += __shfl_xor(l, 16); l += __shfl_xor(l, 32);
;     const float inv = 1.f / l;
;     if (qi[nt] < T_) {
;       const size_t row = (size_t)(b * T_ + qi[nt]);
; #pragma unroll
;       for (int mt = 0; mt < 4; ++mt) {
;         const u32x2 gv = *(const u32x2*)(ws.GATE + row * 1024 + hd * 64 + 16 * mt + 4 * lq);
;         const float o0 = oacc[mt][nt][0] * inv * siluf_(bflo(gv.x)), o1 = oacc[mt][nt][1] * inv * siluf_(bfhi(gv.x));
;         const float o2 = oacc[mt][nt][2] * inv * siluf_(bflo(gv.y)), o3 = oacc[mt][nt][3] * inv * siluf_(bfhi(gv.y));
;         u32x2 pk; pk.x = cvt_pk_bf16(o0, o1); pk.y = cvt_pk_bf16(o2, o3);
;         if (!dry) *(u32x2*)(ws.QB + row * 1536 + hd * 96 + 16 * mt + 4 * lq) = pk;
;       }
;     }
;   }
.LBB0_881:
	v_mbcnt_lo_u32_b32 v250, -1, 0
	v_mbcnt_hi_u32_b32 v250, -1, v250
	s_add_i32 s6, s15, -1
	v_and_b32_e32 v107, 15, v250
	v_lshrrev_b32_e32 v106, 4, v250
	v_lshl_add_u32 v106, v107, 2, v106
	v_lshlrev_b32_e32 v106, 2, v106
	v_and_b32_e32 v107, 3, v250
	v_lshrrev_b32_e32 v250, 2, v250
	v_lshl_add_u32 v250, v107, 4, v250
	v_lshlrev_b32_e32 v250, 2, v250
	v_lshlrev_b32_e32 v110, 1, v182
	v_mov_b32_e32 v111, 0
	v_min_i32_e32 v108, s6, v169
	v_add_u32_e32 v108, s66, v108
	v_ashrrev_i32_e32 v109, 31, v108
	v_lshlrev_b64 v[108:109], 11, v[108:109]
	v_lshl_add_u64 v[108:109], s[54:55], 0, v[108:109]
	v_lshl_add_u64 v[108:109], v[146:147], 1, v[108:109]
	v_lshl_add_u64 v[108:109], v[108:109], 0, v[110:111]
	v_min_i32_e32 v112, s6, v13
	v_add_u32_e32 v112, s66, v112
	v_ashrrev_i32_e32 v113, 31, v112
	v_lshlrev_b64 v[112:113], 11, v[112:113]
	v_lshl_add_u64 v[112:113], s[54:55], 0, v[112:113]
	v_lshl_add_u64 v[112:113], v[146:147], 1, v[112:113]
	v_lshl_add_u64 v[112:113], v[112:113], 0, v[110:111]
	ds_bpermute_b32 v112, v250, v112
	ds_bpermute_b32 v113, v250, v113
	ds_bpermute_b32 v108, v250, v108
	ds_bpermute_b32 v109, v250, v109
	s_waitcnt lgkmcnt(0)
	global_load_dwordx2 v[22:23], v[112:113], off
	global_load_dwordx2 v[24:25], v[112:113], off offset:32
	global_load_dwordx2 v[30:31], v[112:113], off offset:64
	global_load_dwordx2 v[32:33], v[112:113], off offset:96
	global_load_dwordx2 v[98:99], v[108:109], off
	global_load_dwordx2 v[100:101], v[108:109], off offset:32
	global_load_dwordx2 v[102:103], v[108:109], off offset:64
	global_load_dwordx2 v[104:105], v[108:109], off offset:96
	ds_bpermute_b32 v0, v170, v201
	v_cmp_gt_i32_e32 vcc, s15, v169
	s_waitcnt lgkmcnt(0)
	v_add_f32_e32 v1, v201, v0
	ds_bpermute_b32 v2, v168, v1
	v_lshlrev_b32_e32 v0, 1, v182
	s_and_saveexec_b64 s[4:5], vcc
	s_cbranch_execz .LBB0_883
	s_waitcnt lgkmcnt(0)
	v_add_f32_e32 v1, v1, v2
	v_div_scale_f32 v2, s[6:7], v1, v1, 1.0
	v_rcp_f32_e32 v3, v2
	s_mov_b32 s63, s93
	v_fma_f32 v4, -v2, v3, 1.0
	v_fmac_f32_e32 v3, v4, v3
	v_div_scale_f32 v4, vcc, 1.0, v1, 1.0
	v_mul_f32_e32 v5, v4, v3
	v_fma_f32 v6, -v2, v5, v4
	v_fmac_f32_e32 v5, v6, v3
	v_add_u32_e32 v6, s66, v169
	v_fma_f32 v2, -v2, v5, v4
	v_ashrrev_i32_e32 v7, 31, v6
	v_div_fmas_f32 v2, v2, v3, v5
	v_lshlrev_b64 v[4:5], 11, v[6:7]
	v_lshl_add_u64 v[4:5], s[54:55], 0, v[4:5]
	v_div_fixup_f32 v2, v2, v1, 1.0
	v_lshl_add_u64 v[4:5], v[146:147], 1, v[4:5]
	v_mov_b32_e32 v1, v12
	v_lshl_add_u64 v[4:5], v[4:5], 0, v[0:1]
	s_waitcnt vmcnt(3)
	ds_bpermute_b32 v8, v106, v98
	ds_bpermute_b32 v9, v106, v99
	s_waitcnt lgkmcnt(0)
	v_lshlrev_b32_e32 v10, 16, v8
	v_mul_f32_e32 v3, 0xbfb8aa3b, v10
	v_exp_f32_e32 v3, v3
	v_and_b32_e32 v11, 0xffff0000, v8
	v_lshlrev_b32_e32 v8, 16, v9
	v_and_b32_e32 v9, 0xffff0000, v9
	v_add_f32_e32 v3, 1.0, v3
	v_rcp_f32_e32 v14, v3
	v_pk_mul_f32 v[16:17], v[94:95], v[2:3] op_sel_hi:[1,0]
	v_mul_f32_e32 v3, 0xbfb8aa3b, v11
	v_exp_f32_e32 v3, v3
	s_nop 0
	v_add_f32_e32 v3, 1.0, v3
	v_rcp_f32_e32 v15, v3
	v_mul_f32_e32 v3, 0xbfb8aa3b, v8
	v_exp_f32_e32 v3, v3
	v_pk_mul_f32 v[10:11], v[14:15], v[10:11]
	s_nop 0
	v_pk_mul_f32 v[10:11], v[16:17], v[10:11]
	v_add_f32_e32 v3, 1.0, v3
	v_rcp_f32_e32 v14, v3
	v_pk_mul_f32 v[16:17], v[96:97], v[2:3] op_sel_hi:[1,0]
	v_mul_f32_e32 v3, 0xbfb8aa3b, v9
	v_exp_f32_e32 v3, v3
	v_cvt_pk_bf16_f32 v10, v10, v11
	v_add_f32_e32 v3, 1.0, v3
	v_rcp_f32_e32 v15, v3
	s_nop 0
	v_pk_mul_f32 v[8:9], v[14:15], v[8:9]
	s_nop 0
	v_pk_mul_f32 v[8:9], v[16:17], v[8:9]
	v_pk_mul_f32 v[16:17], v[90:91], v[2:3] op_sel_hi:[1,0]
	v_cvt_pk_bf16_f32 v11, v8, v9
	v_mov_b64_e32 v[8:9], s[58:59]
	v_mad_i64_i32 v[6:7], s[6:7], v6, s83, v[8:9]
	v_lshl_add_u64 v[6:7], v[6:7], 0, s[62:63]
	v_lshl_add_u64 v[6:7], v[6:7], 0, v[0:1]
	ds_bpermute_b32 v242, v250, v6
	ds_bpermute_b32 v243, v250, v7
	ds_bpermute_b32 v252, v250, v10
	ds_bpermute_b32 v253, v250, v11
	s_waitcnt vmcnt(2)
	ds_bpermute_b32 v8, v106, v100
	ds_bpermute_b32 v9, v106, v101
	s_waitcnt lgkmcnt(0)
	v_lshlrev_b32_e32 v10, 16, v8
	v_mul_f32_e32 v1, 0xbfb8aa3b, v10
	v_exp_f32_e32 v1, v1
	v_and_b32_e32 v11, 0xffff0000, v8
	v_lshlrev_b32_e32 v8, 16, v9
	v_and_b32_e32 v9, 0xffff0000, v9
	v_add_f32_e32 v1, 1.0, v1
	v_rcp_f32_e32 v14, v1
	v_mul_f32_e32 v1, 0xbfb8aa3b, v11
	v_exp_f32_e32 v1, v1
	s_nop 0
	v_add_f32_e32 v1, 1.0, v1
	v_rcp_f32_e32 v15, v1
	v_mul_f32_e32 v1, 0xbfb8aa3b, v8
	v_exp_f32_e32 v1, v1
	v_pk_mul_f32 v[10:11], v[14:15], v[10:11]
	s_nop 0
	v_pk_mul_f32 v[10:11], v[16:17], v[10:11]
	v_add_f32_e32 v1, 1.0, v1
	v_rcp_f32_e32 v14, v1
	v_mul_f32_e32 v1, 0xbfb8aa3b, v9
	v_exp_f32_e32 v1, v1
	v_pk_mul_f32 v[16:17], v[92:93], v[2:3] op_sel_hi:[1,0]
	v_cvt_pk_bf16_f32 v10, v10, v11
	v_add_f32_e32 v1, 1.0, v1
	v_rcp_f32_e32 v15, v1
	s_nop 0
	v_pk_mul_f32 v[8:9], v[14:15], v[8:9]
	s_nop 0
	v_pk_mul_f32 v[8:9], v[16:17], v[8:9]
	v_pk_mul_f32 v[16:17], v[74:75], v[2:3] op_sel_hi:[1,0]
	v_cvt_pk_bf16_f32 v11, v8, v9
	ds_bpermute_b32 v254, v250, v10
	ds_bpermute_b32 v255, v250, v11
	s_waitcnt lgkmcnt(2)
	global_store_dwordx2 v[242:243], v[252:253], off
	s_waitcnt vmcnt(2)
	ds_bpermute_b32 v8, v106, v102
	ds_bpermute_b32 v9, v106, v103
	s_waitcnt lgkmcnt(0)
; __device__ __forceinline__ float bflo(unsigned v) { return __uint_as_float(v << 16); }
; __device__ __forceinline__ float bfhi(unsigned v) { return __uint_as_float(v & 0xffff0000u); }
; __device__ __forceinline__ float siluf_(float x) { return x * __builtin_amdgcn_rcpf(1.f + __expf(-x)); }
; __device__ __forceinline__ void attn_unit(const WS& ws, int u, bool dry = false) {
;     ...
;       for (int mt = 0; mt < 4; ++mt) {
;         const u32x2 gv = *(const u32x2*)(ws.GATE + row * 1024 + hd * 64 + 16 * mt + 4 * lq);
;         const float o0 = oacc[mt][nt][0] * inv * siluf_(bflo(gv.x)), o1 = oacc[mt][nt][1] * inv * siluf_(bfhi(gv.x));
;         const float o2 = oacc[mt][nt][2] * inv * siluf_(bflo(gv.y)), o3 = oacc[mt][nt][3] * inv * siluf_(bfhi(gv.y));
;         u32x2 pk; pk.x = cvt_pk_bf16(o0, o1); pk.y = cvt_pk_bf16(o2, o3);
;         if (!dry) *(u32x2*)(ws.QB + row * 1536 + hd * 96 + 16 * mt + 4 * lq) = pk;
;       }
	v_lshlrev_b32_e32 v10, 16, v8
	v_mul_f32_e32 v1, 0xbfb8aa3b, v10
	v_exp_f32_e32 v1, v1
	v_and_b32_e32 v11, 0xffff0000, v8
	v_lshlrev_b32_e32 v8, 16, v9
	v_and_b32_e32 v9, 0xffff0000, v9
	v_add_f32_e32 v1, 1.0, v1
	v_rcp_f32_e32 v14, v1
	v_mul_f32_e32 v1, 0xbfb8aa3b, v11
	v_exp_f32_e32 v1, v1
	s_nop 0
	v_add_f32_e32 v1, 1.0, v1
	v_rcp_f32_e32 v15, v1
	v_mul_f32_e32 v1, 0xbfb8aa3b, v8
	v_exp_f32_e32 v1, v1
	v_pk_mul_f32 v[10:11], v[14:15], v[10:11]
	s_nop 0
	v_pk_mul_f32 v[10:11], v[16:17], v[10:11]
	v_add_f32_e32 v1, 1.0, v1
	v_rcp_f32_e32 v14, v1
	v_mul_f32_e32 v1, 0xbfb8aa3b, v9
	v_exp_f32_e32 v1, v1
	v_pk_mul_f32 v[16:17], v[76:77], v[2:3] op_sel_hi:[1,0]
	v_cvt_pk_bf16_f32 v10, v10, v11
	v_add_f32_e32 v1, 1.0, v1
	v_rcp_f32_e32 v15, v1
	s_nop 0
	v_pk_mul_f32 v[8:9], v[14:15], v[8:9]
	s_nop 0
	v_pk_mul_f32 v[8:9], v[16:17], v[8:9]
	v_pk_mul_f32 v[14:15], v[66:67], v[2:3] op_sel_hi:[1,0]
	v_cvt_pk_bf16_f32 v11, v8, v9
	ds_bpermute_b32 v252, v250, v10
	ds_bpermute_b32 v253, v250, v11
	s_waitcnt lgkmcnt(2)
	global_store_dwordx2 v[242:243], v[254:255], off offset:32
	v_pk_mul_f32 v[2:3], v[68:69], v[2:3] op_sel_hi:[1,0]
	s_waitcnt vmcnt(2)
	ds_bpermute_b32 v4, v106, v104
	ds_bpermute_b32 v5, v106, v105
	s_waitcnt lgkmcnt(0)
	v_lshlrev_b32_e32 v8, 16, v4
	v_mul_f32_e32 v1, 0xbfb8aa3b, v8
	v_exp_f32_e32 v1, v1
	v_and_b32_e32 v9, 0xffff0000, v4
	v_lshlrev_b32_e32 v4, 16, v5
	v_and_b32_e32 v5, 0xffff0000, v5
	v_add_f32_e32 v1, 1.0, v1
	v_rcp_f32_e32 v10, v1
	v_mul_f32_e32 v1, 0xbfb8aa3b, v9
	v_exp_f32_e32 v1, v1
	s_nop 0
	v_add_f32_e32 v1, 1.0, v1
	v_rcp_f32_e32 v11, v1
	v_mul_f32_e32 v1, 0xbfb8aa3b, v4
	v_exp_f32_e32 v1, v1
	v_pk_mul_f32 v[8:9], v[10:11], v[8:9]
	s_nop 0
	v_pk_mul_f32 v[8:9], v[14:15], v[8:9]
	v_add_f32_e32 v1, 1.0, v1
	v_rcp_f32_e32 v10, v1
	v_mul_f32_e32 v1, 0xbfb8aa3b, v5
	v_exp_f32_e32 v1, v1
	s_nop 0
	v_add_f32_e32 v1, 1.0, v1
	v_rcp_f32_e32 v11, v1
	s_nop 0
	v_pk_mul_f32 v[4:5], v[10:11], v[4:5]
	s_nop 0
	v_pk_mul_f32 v[2:3], v[2:3], v[4:5]
	v_cvt_pk_bf16_f32 v4, v8, v9
	v_cvt_pk_bf16_f32 v5, v2, v3
	ds_bpermute_b32 v254, v250, v4
	ds_bpermute_b32 v255, v250, v5
	s_waitcnt lgkmcnt(2)
	global_store_dwordx2 v[242:243], v[252:253], off offset:64
	s_waitcnt lgkmcnt(0)
	global_store_dwordx2 v[242:243], v[254:255], off offset:96
; __device__ __forceinline__ float bflo(unsigned v) { return __uint_as_float(v << 16); }
; __device__ __forceinline__ float bfhi(unsigned v) { return __uint_as_float(v & 0xffff0000u); }
; __device__ __forceinline__ float siluf_(float x) { return x * __builtin_amdgcn_rcpf(1.f + __expf(-x)); }
; __device__ __forceinline__ void attn_unit(const WS& ws, int u, bool dry = false) {
;     ...
;   for (int nt = 0; nt < 2; ++nt) {
;     float l = lsum[nt];
;     l += __shfl_xor(l, 16); l += __shfl_xor(l, 32);
;     const float inv = 1.f / l;
;     if (qi[nt] < T_) {
;       const size_t row = (size_t)(b * T_ + qi[nt]);
; #pragma unroll
;       for (int mt = 0; mt < 4; ++mt) {
;         const u32x2 gv = *(const u32x2*)(ws.GATE + row * 1024 + hd * 64 + 16 * mt + 4 * lq);
;         const float o0 = oacc[mt][nt][0] * inv * siluf_(bflo(gv.x)), o1 = oacc[mt][nt][1] * inv * siluf_(bfhi(gv.x));
;         const float o2 = oacc[mt][nt][2] * inv * siluf_(bflo(gv.y)), o3 = oacc[mt][nt][3] * inv * siluf_(bfhi(gv.y));
;         u32x2 pk; pk.x = cvt_pk_bf16(o0, o1); pk.y = cvt_pk_bf16(o2, o3);
;         if (!dry) *(u32x2*)(ws.QB + row * 1536 + hd * 96 + 16 * mt + 4 * lq) = pk;
;       }
;     }
;   }
.LBB0_883:
	s_or_b64 exec, exec, s[4:5]
	ds_bpermute_b32 v1, v170, v176
	v_cmp_gt_i32_e32 vcc, s15, v13
	s_waitcnt lgkmcnt(0)
	v_add_f32_e32 v1, v176, v1
	ds_bpermute_b32 v2, v168, v1
	s_and_saveexec_b64 s[4:5], vcc
	s_cbranch_execz .LBB0_835
	s_waitcnt lgkmcnt(0)
	v_add_f32_e32 v1, v1, v2
	v_div_scale_f32 v2, s[6:7], v1, v1, 1.0
	v_rcp_f32_e32 v3, v2
	s_mov_b32 s63, s93
	v_fma_f32 v4, -v2, v3, 1.0
	v_fmac_f32_e32 v3, v4, v3
	v_div_scale_f32 v4, vcc, 1.0, v1, 1.0
	v_mul_f32_e32 v5, v4, v3
	v_fma_f32 v6, -v2, v5, v4
	v_fmac_f32_e32 v5, v6, v3
	v_add_u32_e32 v6, s66, v13
	v_fma_f32 v2, -v2, v5, v4
	v_ashrrev_i32_e32 v7, 31, v6
	v_div_fmas_f32 v2, v2, v3, v5
	v_lshlrev_b64 v[4:5], 11, v[6:7]
	v_lshl_add_u64 v[4:5], s[54:55], 0, v[4:5]
	v_div_fixup_f32 v2, v2, v1, 1.0
	v_lshl_add_u64 v[4:5], v[146:147], 1, v[4:5]
	v_mov_b32_e32 v1, v12
	v_lshl_add_u64 v[4:5], v[4:5], 0, v[0:1]
	s_waitcnt vmcnt(4)
	ds_bpermute_b32 v8, v106, v22
	ds_bpermute_b32 v9, v106, v23
	s_waitcnt lgkmcnt(0)
	v_lshlrev_b32_e32 v10, 16, v8
	v_mul_f32_e32 v3, 0xbfb8aa3b, v10
	v_exp_f32_e32 v3, v3
	v_and_b32_e32 v11, 0xffff0000, v8
	v_lshlrev_b32_e32 v8, 16, v9
	v_and_b32_e32 v9, 0xffff0000, v9
	v_add_f32_e32 v3, 1.0, v3
	v_rcp_f32_e32 v14, v3
	v_pk_mul_f32 v[16:17], v[62:63], v[2:3] op_sel_hi:[1,0]
	v_mul_f32_e32 v3, 0xbfb8aa3b, v11
	v_exp_f32_e32 v3, v3
	s_nop 0
	v_add_f32_e32 v3, 1.0, v3
	v_rcp_f32_e32 v15, v3
	v_mul_f32_e32 v3, 0xbfb8aa3b, v8
	v_exp_f32_e32 v3, v3
	v_pk_mul_f32 v[10:11], v[14:15], v[10:11]
	s_nop 0
	v_pk_mul_f32 v[10:11], v[16:17], v[10:11]
	v_add_f32_e32 v3, 1.0, v3
	v_rcp_f32_e32 v14, v3
	v_pk_mul_f32 v[16:17], v[64:65], v[2:3] op_sel_hi:[1,0]
	v_mul_f32_e32 v3, 0xbfb8aa3b, v9
	v_exp_f32_e32 v3, v3
	v_cvt_pk_bf16_f32 v10, v10, v11
	v_add_f32_e32 v3, 1.0, v3
	v_rcp_f32_e32 v15, v3
	s_nop 0
	v_pk_mul_f32 v[8:9], v[14:15], v[8:9]
	s_nop 0
	v_pk_mul_f32 v[8:9], v[16:17], v[8:9]
	s_nop 0
	v_cvt_pk_bf16_f32 v11, v8, v9
	v_mov_b64_e32 v[8:9], s[58:59]
	v_mad_i64_i32 v[6:7], s[6:7], v6, s83, v[8:9]
	v_lshl_add_u64 v[6:7], v[6:7], 0, s[62:63]
	v_lshl_add_u64 v[0:1], v[6:7], 0, v[0:1]
	ds_bpermute_b32 v242, v250, v0
	ds_bpermute_b32 v243, v250, v1
	ds_bpermute_b32 v252, v250, v10
	ds_bpermute_b32 v253, v250, v11
	s_waitcnt vmcnt(4)
	ds_bpermute_b32 v6, v106, v24
	ds_bpermute_b32 v7, v106, v25
	s_waitcnt lgkmcnt(0)
	v_lshlrev_b32_e32 v8, 16, v6
	v_mul_f32_e32 v3, 0xbfb8aa3b, v8
	v_exp_f32_e32 v3, v3
	v_and_b32_e32 v9, 0xffff0000, v6
	v_lshlrev_b32_e32 v6, 16, v7
	v_and_b32_e32 v7, 0xffff0000, v7
	v_add_f32_e32 v3, 1.0, v3
	v_rcp_f32_e32 v10, v3
	v_pk_mul_f32 v[14:15], v[46:47], v[2:3] op_sel_hi:[1,0]
	v_mul_f32_e32 v3, 0xbfb8aa3b, v9
	v_exp_f32_e32 v3, v3
	s_nop 0
	v_add_f32_e32 v3, 1.0, v3
	v_rcp_f32_e32 v11, v3
	v_mul_f32_e32 v3, 0xbfb8aa3b, v6
	v_exp_f32_e32 v3, v3
	v_pk_mul_f32 v[8:9], v[10:11], v[8:9]
	s_nop 0
	v_pk_mul_f32 v[8:9], v[14:15], v[8:9]
	v_add_f32_e32 v3, 1.0, v3
	v_rcp_f32_e32 v10, v3
	v_pk_mul_f32 v[14:15], v[48:49], v[2:3] op_sel_hi:[1,0]
	v_mul_f32_e32 v3, 0xbfb8aa3b, v7
	v_exp_f32_e32 v3, v3
	v_cvt_pk_bf16_f32 v8, v8, v9
	v_add_f32_e32 v3, 1.0, v3
	v_rcp_f32_e32 v11, v3
	s_nop 0
	v_pk_mul_f32 v[6:7], v[10:11], v[6:7]
	s_nop 0
	v_pk_mul_f32 v[6:7], v[14:15], v[6:7]
	s_nop 0
	v_cvt_pk_bf16_f32 v9, v6, v7
	ds_bpermute_b32 v254, v250, v8
	ds_bpermute_b32 v255, v250, v9
	s_waitcnt lgkmcnt(2)
	global_store_dwordx2 v[242:243], v[252:253], off
	s_waitcnt vmcnt(5)
	ds_bpermute_b32 v6, v106, v30
	ds_bpermute_b32 v7, v106, v31
	s_waitcnt lgkmcnt(0)
	v_lshlrev_b32_e32 v8, 16, v6
	v_mul_f32_e32 v3, 0xbfb8aa3b, v8
	v_exp_f32_e32 v3, v3
	v_and_b32_e32 v9, 0xffff0000, v6
	v_lshlrev_b32_e32 v6, 16, v7
	v_and_b32_e32 v7, 0xffff0000, v7
	v_add_f32_e32 v3, 1.0, v3
	v_rcp_f32_e32 v10, v3
	v_pk_mul_f32 v[14:15], v[38:39], v[2:3] op_sel_hi:[1,0]
	v_mul_f32_e32 v3, 0xbfb8aa3b, v9
	v_exp_f32_e32 v3, v3
	s_nop 0
	v_add_f32_e32 v3, 1.0, v3
	v_rcp_f32_e32 v11, v3
	v_mul_f32_e32 v3, 0xbfb8aa3b, v6
	v_exp_f32_e32 v3, v3
	v_pk_mul_f32 v[8:9], v[10:11], v[8:9]
	s_nop 0
	v_pk_mul_f32 v[8:9], v[14:15], v[8:9]
	v_add_f32_e32 v3, 1.0, v3
	v_rcp_f32_e32 v10, v3
	v_pk_mul_f32 v[14:15], v[40:41], v[2:3] op_sel_hi:[1,0]
	v_mul_f32_e32 v3, 0xbfb8aa3b, v7
	v_exp_f32_e32 v3, v3
	v_cvt_pk_bf16_f32 v8, v8, v9
	v_add_f32_e32 v3, 1.0, v3
	v_rcp_f32_e32 v11, v3
	s_nop 0
	v_pk_mul_f32 v[6:7], v[10:11], v[6:7]
	s_nop 0
	v_pk_mul_f32 v[6:7], v[14:15], v[6:7]
	s_nop 0
	v_cvt_pk_bf16_f32 v9, v6, v7
	ds_bpermute_b32 v252, v250, v8
	ds_bpermute_b32 v253, v250, v9
	s_waitcnt lgkmcnt(2)
	global_store_dwordx2 v[242:243], v[254:255], off offset:32
	s_waitcnt vmcnt(6)
	ds_bpermute_b32 v4, v106, v32
	ds_bpermute_b32 v5, v106, v33
	s_waitcnt lgkmcnt(0)
	v_lshlrev_b32_e32 v6, 16, v4
	v_mul_f32_e32 v3, 0xbfb8aa3b, v6
	v_exp_f32_e32 v3, v3
	v_and_b32_e32 v7, 0xffff0000, v4
	v_lshlrev_b32_e32 v4, 16, v5
	v_and_b32_e32 v5, 0xffff0000, v5
	v_add_f32_e32 v3, 1.0, v3
	v_rcp_f32_e32 v8, v3
	v_pk_mul_f32 v[10:11], v[34:35], v[2:3] op_sel_hi:[1,0]
	v_mul_f32_e32 v3, 0xbfb8aa3b, v7
	v_exp_f32_e32 v3, v3
	s_nop 0
	v_add_f32_e32 v3, 1.0, v3
	v_rcp_f32_e32 v9, v3
	v_mul_f32_e32 v3, 0xbfb8aa3b, v4
	v_exp_f32_e32 v3, v3
	v_pk_mul_f32 v[6:7], v[8:9], v[6:7]
	v_mul_f32_e32 v9, 0xbfb8aa3b, v5
	v_exp_f32_e32 v9, v9
	v_add_f32_e32 v3, 1.0, v3
	v_rcp_f32_e32 v8, v3
	v_pk_mul_f32 v[2:3], v[36:37], v[2:3] op_sel_hi:[1,0]
	v_add_f32_e32 v9, 1.0, v9
	v_rcp_f32_e32 v9, v9
	v_pk_mul_f32 v[6:7], v[10:11], v[6:7]
	v_pk_mul_f32 v[4:5], v[8:9], v[4:5]
	s_nop 0
	v_pk_mul_f32 v[2:3], v[2:3], v[4:5]
	v_cvt_pk_bf16_f32 v4, v6, v7
	v_cvt_pk_bf16_f32 v5, v2, v3
	ds_bpermute_b32 v254, v250, v4
	ds_bpermute_b32 v255, v250, v5
	s_waitcnt lgkmcnt(2)
	global_store_dwordx2 v[242:243], v[252:253], off offset:64
	s_waitcnt lgkmcnt(0)
	global_store_dwordx2 v[242:243], v[254:255], off offset:96
	s_branch .LBB0_835
